# conv-tail schedule B: only W1 of layer 0 in the prologue; remaining images spread over the idle last-round workgroups of phases 1,3,7,10,12,14
# speedup vs baseline: 1.0170x; 1.0029x over previous
.LBB0_76:
	s_mov_b32 s98, 0
	s_mov_b32 s17, 0x1
	s_cmp_eq_u32 s88, 0
	s_cbranch_scc1 .LBB0_81
	s_mov_b32 s17, 0
	s_mov_b32 s99, 0
	s_cmp_eq_u32 s88, 1
	s_cselect_b32 s17, 0x6, s17
	s_cselect_b32 s99, 0x96, s99
	s_cmp_eq_u32 s88, 3
	s_cselect_b32 s17, 0x50, s17
	s_cselect_b32 s99, 0x8e, s99
	s_cmp_eq_u32 s88, 7
	s_cselect_b32 s17, 0x28, s17
	s_cselect_b32 s99, 0xd3, s99
	s_cmp_eq_u32 s88, 10
	s_cselect_b32 s17, 0x180, s17
	s_cselect_b32 s99, 0x96, s99
	s_cmp_eq_u32 s88, 12
	s_cselect_b32 s17, 0x600, s17
	s_cselect_b32 s99, 0x96, s99
	s_cmp_eq_u32 s88, 14
	s_cselect_b32 s17, 0x800, s17
	s_cselect_b32 s99, 0x8e, s99
	s_cmp_eq_u32 s17, 0
	s_cbranch_scc1 .LBB0_78
	s_cmp_lt_u32 s2, s99
	s_cbranch_scc0 .Lcv_idle

.LBB0_606:
	s_and_b64 vcc, exec, s[0:1]
	s_cbranch_vccz .LBB0_508
	s_waitcnt vmcnt(0)
	v_lshrrev_b32_e32 v90, 4, v241
	v_bfe_u32 v91, v241, 3, 1
	v_and_b32_e32 v86, 15, v241
	v_lshlrev_b32_e32 v90, 1, v90
	v_lshlrev_b32_e32 v86, 4, v86
	v_add_u32_e32 v92, v90, v91
	v_xor_b32_e32 v91, 1, v91
	v_add_u32_e32 v93, v90, v91
	s_lshl_b32 s0, s10, 5
	v_lshlrev_b32_e32 v89, 2, v92
	v_add_u32_e32 v92, s0, v92
	v_add_u32_e32 v93, s0, v93
	v_add_u32_e32 v89, 0x18000, v89
	v_lshlrev_b32_e32 v87, 2, v92
	v_lshlrev_b32_e32 v88, 2, v93
	v_mov_b32_e32 v0, 0
	v_mov_b32_e32 v1, 0
	v_mov_b32_e32 v2, 0
	v_mov_b32_e32 v3, 0
	v_mov_b32_e32 v4, 0
	v_mov_b32_e32 v5, 0
	v_mov_b32_e32 v6, 0
	v_mov_b32_e32 v7, 0
	s_waitcnt lgkmcnt(0)
	s_barrier
	s_mov_b32 s4, 0
	s_nop 0
	s_nop 0
	s_nop 0
	s_nop 0
	s_nop 0
	s_nop 0
	s_nop 0
	s_nop 0
	s_nop 0
	s_nop 0
	s_nop 0
	s_nop 0
	s_nop 0
	s_nop 0
	s_nop 0
	s_nop 0
